# adds static s_setprio 1 for waves 4-7 during the NSA attention phase (on top of GEMM static priority)
# speedup vs baseline: 1.0044x; 1.0044x over previous
.LBB0_210:
	s_add_u32 s6, s58, 0x23900000
	s_addc_u32 s7, s59, 0
	s_cmp_gt_i32 s78, 11
	s_mov_b64 s[0:1], -1
	s_cbranch_scc0 .LBB0_406
	v_writelane_b32 v254, s0, 33
	s_cmp_eq_u32 s78, 12
	s_nop 0
	v_writelane_b32 v254, s1, 34
	s_cbranch_scc0 .LBB0_405
	v_writelane_b32 v254, s6, 54
	s_nop 1
	v_writelane_b32 v254, s7, 55
	v_writelane_b32 v254, s82, 52
	s_nop 1
	v_writelane_b32 v254, s83, 53
	s_nop 0
	v_readlane_b32 s0, v254, 37
	s_cmpk_gt_i32 s0, 0x7ff
	v_readlane_b32 s1, v254, 38
	s_cbranch_scc1 .LBB0_404
	s_add_u32 s82, s58, 0x27a00000
	s_addc_u32 s83, s59, 0
	s_lshl_b32 s0, s64, 11
	v_lshlrev_b32_e32 v0, 1, v168
	s_waitcnt lgkmcnt(0)
	v_lshrrev_b32_e32 v3, 1, v166
	s_add_i32 s70, s0, 0
	v_and_b32_e32 v0, 8, v0
	v_and_b32_e32 v2, 19, v166
	v_and_b32_e32 v3, 4, v3
	v_lshrrev_b32_e32 v6, 5, v168
	v_readlane_b32 s0, v254, 23
	v_or3_b32 v3, v3, v2, v0
	v_lshlrev_b32_e32 v0, 6, v6
	v_readlane_b32 s1, v254, 24
	v_ashrrev_i32_e32 v176, 3, v166
	v_ashrrev_i32_e32 v177, 31, v176
	v_lshl_add_u64 v[174:175], s[0:1], 0, v[0:1]
	v_readlane_b32 s0, v254, 54
	v_lshlrev_b64 v[4:5], 9, v[176:177]
	v_readlane_b32 s1, v254, 55
	s_waitcnt vmcnt(0)
	v_and_b32_e32 v195, 7, v166
	s_ashr_i32 s34, s63, 5
	v_lshl_add_u64 v[178:179], s[0:1], 0, v[4:5]
	s_movk_i32 s0, 0x90
	v_mul_lo_u32 v0, v176, s0
	v_readlane_b32 s0, v254, 31
	v_lshlrev_b32_e32 v170, 4, v6
	v_mov_b32_e32 v171, v1
	v_lshlrev_b32_e32 v4, 4, v195
	v_readlane_b32 s1, v254, 32
	v_and_b32_e32 v7, 31, v166
	s_cmpk_eq_i32 s63, 0x100
	v_add3_u32 v203, 0, v0, v4
	v_lshl_add_u64 v[4:5], s[0:1], 0, v[170:171]
	s_mul_i32 s0, s64, 0xfffff840
	s_cselect_b64 s[84:85], -1, 0
	v_lshlrev_b32_e32 v0, 9, v7
	v_mul_u32_u24_e32 v204, 0x90, v3
	v_lshl_add_u32 v3, v7, 8, s70
	v_lshl_add_u32 v206, v168, 2, s70
	s_add_i32 s70, s70, s0
	v_readlane_b32 s0, v254, 46
	v_lshl_add_u64 v[180:181], v[4:5], 0, v[0:1]
	v_lshlrev_b64 v[4:5], 13, v[176:177]
	v_readlane_b32 s1, v254, 47
	s_abs_i32 s88, s63
	v_lshlrev_b32_e32 v2, 3, v195
	v_lshl_add_u64 v[182:183], s[0:1], 0, v[4:5]
	v_readlane_b32 s0, v254, 48
	v_readlane_b32 s1, v254, 49
	v_lshlrev_b32_e32 v0, 2, v6
	s_lshl_b32 s35, s64, 3
	v_lshl_add_u64 v[184:185], s[0:1], 0, v[4:5]
	v_cvt_f32_u32_e32 v4, s88
	s_sub_i32 s0, 0, s88
	v_bfe_u32 v201, v166, 3, 2
	v_cmp_eq_u32_e64 s[2:3], 0, v166
	v_rcp_iflag_f32_e32 v4, v4
	v_lshlrev_b32_e32 v202, 3, v6
	v_lshl_add_u64 v[172:173], s[96:97], 0, v[170:171]
	v_mul_u32_u24_e32 v171, 0x90, v7
	v_mul_f32_e32 v4, 0x4f7ffffe, v4
	v_cvt_u32_f32_e32 v4, v4
	v_cmp_gt_u32_e64 s[4:5], 8, v7
	v_cmp_eq_u32_e64 s[6:7], 0, v168
	v_add_u32_e32 v207, 1, v168
	v_readfirstlane_b32 s1, v4
	s_mul_i32 s0, s0, s1
	s_mul_hi_u32 s0, s1, s0
	s_add_i32 s89, s1, s0
	v_readlane_b32 s0, v254, 37
	v_add_u32_e32 v208, s70, v2
	s_ashr_i32 s71, s63, 31
	v_lshlrev_b32_e32 v186, 1, v2
	v_lshlrev_b32_e32 v188, 1, v0
	v_add_u32_e32 v177, v3, v170
	s_mov_b32 s90, s0
	v_readlane_b32 s1, v254, 38
	v_readfirstlane_b32 vcc_lo, v169
	s_nop 0
	s_bitcmp1_b32 vcc_lo, 8
	s_cbranch_scc0 .Lattn_prio_skip
	s_setprio 1
.Lattn_prio_skip:
	s_branch .LBB0_215
.LBB0_214:
	v_mul_f32_e32 v0, 0xbfb8aa3b, v155
	v_exp_f32_e32 v0, v0
	s_waitcnt lgkmcnt(0)
	s_barrier
	v_add_f32_e32 v0, 1.0, v0
	v_div_scale_f32 v98, s[0:1], v0, v0, 1.0
	v_rcp_f32_e32 v99, v98
	s_add_i32 s90, s90, s63
	s_cmpk_gt_i32 s90, 0x7ff
	v_fma_f32 v100, -v98, v99, 1.0
	v_fmac_f32_e32 v99, v100, v99
	v_div_scale_f32 v100, vcc, 1.0, v0, 1.0
	v_mul_f32_e32 v101, v100, v99
	v_fma_f32 v102, -v98, v101, v100
	v_fmac_f32_e32 v101, v102, v99
	v_fma_f32 v98, -v98, v101, v100
	v_div_fmas_f32 v98, v98, v99, v101
	v_div_fixup_f32 v0, v98, v0, 1.0
	v_add_f32_e32 v98, v146, v148
	v_div_scale_f32 v99, s[0:1], v98, v98, v0
	v_rcp_f32_e32 v100, v99
	s_nop 0
	v_fma_f32 v101, -v99, v100, 1.0
	v_fmac_f32_e32 v100, v101, v100
	v_div_scale_f32 v101, vcc, v0, v98, v0
	v_mul_f32_e32 v102, v101, v100
	v_fma_f32 v103, -v99, v102, v101
	v_fmac_f32_e32 v102, v103, v100
	v_fma_f32 v99, -v99, v102, v101
	v_div_fmas_f32 v99, v99, v100, v102
	v_div_fixup_f32 v0, v99, v98, v0
	v_pk_mul_f32 v[34:35], v[34:35], v[0:1] op_sel_hi:[1,0]
	v_pk_mul_f32 v[50:51], v[50:51], v[0:1] op_sel_hi:[1,0]
	v_pk_mul_f32 v[36:37], v[36:37], v[0:1] op_sel_hi:[1,0]
	v_pk_mul_f32 v[52:53], v[52:53], v[0:1] op_sel_hi:[1,0]
	v_pk_mul_f32 v[38:39], v[38:39], v[0:1] op_sel_hi:[1,0]
	v_pk_mul_f32 v[54:55], v[54:55], v[0:1] op_sel_hi:[1,0]
	v_pk_mul_f32 v[40:41], v[40:41], v[0:1] op_sel_hi:[1,0]
	v_pk_mul_f32 v[56:57], v[56:57], v[0:1] op_sel_hi:[1,0]
	v_pk_mul_f32 v[42:43], v[42:43], v[0:1] op_sel_hi:[1,0]
	v_pk_mul_f32 v[58:59], v[58:59], v[0:1] op_sel_hi:[1,0]
	v_pk_mul_f32 v[44:45], v[44:45], v[0:1] op_sel_hi:[1,0]
	v_pk_mul_f32 v[60:61], v[60:61], v[0:1] op_sel_hi:[1,0]
	v_pk_mul_f32 v[46:47], v[46:47], v[0:1] op_sel_hi:[1,0]
	v_pk_mul_f32 v[62:63], v[62:63], v[0:1] op_sel_hi:[1,0]
	v_pk_mul_f32 v[48:49], v[48:49], v[0:1] op_sel_hi:[1,0]
	v_pk_mul_f32 v[64:65], v[64:65], v[0:1] op_sel_hi:[1,0]
	v_mul_f32_e32 v0, 0xbfb8aa3b, v156
	v_exp_f32_e32 v0, v0
	s_nop 0
	v_add_f32_e32 v0, 1.0, v0
	v_div_scale_f32 v98, s[0:1], v0, v0, 1.0
	v_rcp_f32_e32 v99, v98
	s_nop 0
	v_fma_f32 v100, -v98, v99, 1.0
	v_fmac_f32_e32 v99, v100, v99
	v_div_scale_f32 v100, vcc, 1.0, v0, 1.0
	v_mul_f32_e32 v101, v100, v99
	v_fma_f32 v102, -v98, v101, v100
	v_fmac_f32_e32 v101, v102, v99
	v_fma_f32 v98, -v98, v101, v100
	v_div_fmas_f32 v98, v98, v99, v101
	v_div_fixup_f32 v98, v98, v0, 1.0
	v_mul_f32_e32 v0, 0xbfb8aa3b, v154
	v_exp_f32_e32 v0, v0
	s_nop 0
	v_add_f32_e32 v0, 1.0, v0
	v_div_scale_f32 v99, s[0:1], v0, v0, 1.0
	v_rcp_f32_e32 v100, v99
	s_nop 0
	v_fma_f32 v101, -v99, v100, 1.0
	v_fmac_f32_e32 v100, v101, v100
	v_div_scale_f32 v101, vcc, 1.0, v0, 1.0
	v_mul_f32_e32 v102, v101, v100
	v_fma_f32 v103, -v99, v102, v101
	v_fmac_f32_e32 v102, v103, v100
	v_fma_f32 v99, -v99, v102, v101
	v_div_fmas_f32 v99, v99, v100, v102
	v_div_fixup_f32 v0, v99, v0, 1.0
	v_mul_f32_e32 v0, v0, v140
	v_pk_fma_f32 v[2:3], v[2:3], v[0:1], v[34:35] op_sel_hi:[1,0,1]
	v_pk_fma_f32 v[18:19], v[18:19], v[0:1], v[50:51] op_sel_hi:[1,0,1]
	v_pk_fma_f32 v[4:5], v[4:5], v[0:1], v[36:37] op_sel_hi:[1,0,1]
	v_pk_fma_f32 v[20:21], v[20:21], v[0:1], v[52:53] op_sel_hi:[1,0,1]
	v_pk_fma_f32 v[6:7], v[6:7], v[0:1], v[38:39] op_sel_hi:[1,0,1]
	v_pk_fma_f32 v[22:23], v[22:23], v[0:1], v[54:55] op_sel_hi:[1,0,1]
	v_pk_fma_f32 v[8:9], v[8:9], v[0:1], v[40:41] op_sel_hi:[1,0,1]
	v_pk_fma_f32 v[24:25], v[24:25], v[0:1], v[56:57] op_sel_hi:[1,0,1]
	v_pk_fma_f32 v[10:11], v[10:11], v[0:1], v[42:43] op_sel_hi:[1,0,1]
	v_pk_fma_f32 v[26:27], v[26:27], v[0:1], v[58:59] op_sel_hi:[1,0,1]
	v_pk_fma_f32 v[12:13], v[12:13], v[0:1], v[44:45] op_sel_hi:[1,0,1]
	v_pk_fma_f32 v[28:29], v[28:29], v[0:1], v[60:61] op_sel_hi:[1,0,1]
	v_pk_fma_f32 v[14:15], v[14:15], v[0:1], v[46:47] op_sel_hi:[1,0,1]
	v_pk_fma_f32 v[30:31], v[30:31], v[0:1], v[62:63] op_sel_hi:[1,0,1]
	v_pk_fma_f32 v[16:17], v[16:17], v[0:1], v[48:49] op_sel_hi:[1,0,1]
	v_pk_fma_f32 v[32:33], v[32:33], v[0:1], v[64:65] op_sel_hi:[1,0,1]
	v_mov_b32_e32 v0, v222
	s_nop 0
	v_lshlrev_b32_e32 v0, 2, v0
	v_xor_b32_e32 v0, 0x80, v0
	ds_bpermute_b32 v0, v0, v147
	s_waitcnt lgkmcnt(0)
	v_add_f32_e32 v0, v147, v0
	v_div_scale_f32 v34, s[0:1], v0, v0, v98
	v_rcp_f32_e32 v35, v34
	v_readlane_b32 s0, v254, 21
	v_readlane_b32 s1, v254, 22
	v_fma_f32 v36, -v34, v35, 1.0
	v_fmac_f32_e32 v35, v36, v35
	v_div_scale_f32 v36, vcc, v98, v0, v98
	v_mul_f32_e32 v37, v36, v35
	v_fma_f32 v38, -v34, v37, v36
	v_fmac_f32_e32 v37, v38, v35
	v_fma_f32 v34, -v34, v37, v36
	v_div_fmas_f32 v34, v34, v35, v37
	v_lshlrev_b64 v[36:37], 11, v[190:191]
	v_div_fixup_f32 v34, v34, v0, v98
	v_lshl_add_u64 v[36:37], s[0:1], 0, v[36:37]
	v_lshlrev_b32_e32 v0, 7, v189
	v_lshl_add_u64 v[36:37], v[36:37], 0, v[0:1]
	v_mov_b32_e32 v189, v1
	v_pk_fma_f32 v[2:3], v[82:83], v[34:35], v[2:3] op_sel_hi:[1,0,1]
	v_pk_fma_f32 v[4:5], v[84:85], v[34:35], v[4:5] op_sel_hi:[1,0,1]
	v_lshl_add_u64 v[36:37], v[36:37], 0, v[188:189]
	v_cvt_pk_bf16_f32 v2, v2, v3
	v_cvt_pk_bf16_f32 v3, v4, v5
	global_store_dwordx2 v[36:37], v[2:3], off
	v_pk_fma_f32 v[2:3], v[86:87], v[34:35], v[6:7] op_sel_hi:[1,0,1]
	v_pk_fma_f32 v[4:5], v[88:89], v[34:35], v[8:9] op_sel_hi:[1,0,1]
	v_cvt_pk_bf16_f32 v2, v2, v3
	v_cvt_pk_bf16_f32 v3, v4, v5
	global_store_dwordx2 v[36:37], v[2:3], off offset:16
	v_pk_fma_f32 v[2:3], v[90:91], v[34:35], v[10:11] op_sel_hi:[1,0,1]
	v_pk_fma_f32 v[4:5], v[92:93], v[34:35], v[12:13] op_sel_hi:[1,0,1]
	v_cvt_pk_bf16_f32 v2, v2, v3
	v_cvt_pk_bf16_f32 v3, v4, v5
	global_store_dwordx2 v[36:37], v[2:3], off offset:32
	v_pk_fma_f32 v[2:3], v[94:95], v[34:35], v[14:15] op_sel_hi:[1,0,1]
	v_pk_fma_f32 v[4:5], v[96:97], v[34:35], v[16:17] op_sel_hi:[1,0,1]
	v_cvt_pk_bf16_f32 v2, v2, v3
	v_cvt_pk_bf16_f32 v3, v4, v5
	global_store_dwordx2 v[36:37], v[2:3], off offset:48
	v_pk_fma_f32 v[2:3], v[66:67], v[34:35], v[18:19] op_sel_hi:[1,0,1]
	v_pk_fma_f32 v[4:5], v[68:69], v[34:35], v[20:21] op_sel_hi:[1,0,1]
	v_cvt_pk_bf16_f32 v2, v2, v3
	v_cvt_pk_bf16_f32 v3, v4, v5
	global_store_dwordx2 v[36:37], v[2:3], off offset:64
	v_pk_fma_f32 v[2:3], v[70:71], v[34:35], v[22:23] op_sel_hi:[1,0,1]
	v_pk_fma_f32 v[4:5], v[72:73], v[34:35], v[24:25] op_sel_hi:[1,0,1]
	v_cvt_pk_bf16_f32 v2, v2, v3
	v_cvt_pk_bf16_f32 v3, v4, v5
	global_store_dwordx2 v[36:37], v[2:3], off offset:80
	v_pk_fma_f32 v[2:3], v[74:75], v[34:35], v[26:27] op_sel_hi:[1,0,1]
	v_pk_fma_f32 v[4:5], v[76:77], v[34:35], v[28:29] op_sel_hi:[1,0,1]
	v_cvt_pk_bf16_f32 v2, v2, v3
	v_cvt_pk_bf16_f32 v3, v4, v5
	global_store_dwordx2 v[36:37], v[2:3], off offset:96
	v_pk_fma_f32 v[2:3], v[78:79], v[34:35], v[30:31] op_sel_hi:[1,0,1]
	v_pk_fma_f32 v[4:5], v[80:81], v[34:35], v[32:33] op_sel_hi:[1,0,1]
	v_cvt_pk_bf16_f32 v2, v2, v3
	v_cvt_pk_bf16_f32 v3, v4, v5
	global_store_dwordx2 v[36:37], v[2:3], off offset:112
	s_cbranch_scc1 .LBB0_404

.LBB0_1245:
	s_setprio 0
	v_readlane_b32 s2, v252, 25
	v_readlane_b32 s3, v252, 26
	s_and_b64 vcc, exec, s[2:3]
	s_cbranch_vccz .LBB0_1300
	s_waitcnt vmcnt(0)
	s_waitcnt vmcnt(0) lgkmcnt(0)
	s_barrier
	s_mov_b64 s[0:1], exec
	v_readlane_b32 s2, v252, 2
	v_readlane_b32 s3, v252, 3
	s_and_b64 s[2:3], s[0:1], s[2:3]
	s_mov_b64 exec, s[2:3]
	s_cbranch_execz .LBB0_1299
	v_readlane_b32 s2, v253, 54
	s_waitcnt vmcnt(0) expcnt(0) lgkmcnt(0)
	s_nop 0
	v_mov_b32_e32 v0, s2
	ds_read_b32 v3, v0
	v_readlane_b32 s2, v253, 55
	s_waitcnt lgkmcnt(0)
	v_cmp_ne_u32_e32 vcc, 0, v3
	v_mov_b32_e32 v0, s2
	ds_read_b32 v2, v0
	s_cbranch_vccnz .LBB0_1263
	s_mov_b32 s8, 1
	s_branch .LBB0_1250
